# GEMM0 epilogue stores widened: 8 lanes x 16 B per row (dwordx4), 8 rows per instruction, half the store and ssq-load instructions
# baseline (speedup 1.0000x reference)
; DI unsigned pk2(float lo, float hi) { f32x2 v = {lo, hi}; bfv2 b = __builtin_convertvector(v, bfv2); return __builtin_bit_cast(unsigned, b); }
; template <int MODE>
; DI void gemm_phase(const Params& p, int layer, unsigned char* lds) {
;     ...
;   for (int li = start; li < total; li += stride) {
;     int mt, nt;
;     if (xmap) { const int per_mg = 8 * n_nt, mg = li / per_mg, rem = li - mg * per_mg; nt = rem >> 3; mt = (mg * 8 + (rem & 7)) * 8 + xid; }
;     else { mt = li / n_nt; nt = li % n_nt; }
;     const int m0 = mt * 256, n0 = nt * 128;
;     f32x16 acc[2][4];
; #pragma unroll
;     for (int a = 0; a < 2; ++a)
; #pragma unroll
;       for (int b = 0; b < 4; ++b)
; #pragma unroll
;         for (int i = 0; i < 16; ++i) acc[a][b][i] = 0.f;
;     const int wu = __builtin_amdgcn_readfirstlane(wid);
;     const int swr = (r >> 2) & 3;
;     const int fo0 = ((0 + hh) ^ swr) * 8, fo1 = ((2 + hh) ^ swr) * 8;
;     ...
;     G_DMA(0, 0); G_DMA(1, 1);
;     asm volatile("s_waitcnt vmcnt(6)" ::: "memory"); __builtin_amdgcn_s_barrier(); asm volatile("" ::: "memory");
;     ...
;             const float rs = rsqrtf(ssq[layer * T_TOK + row] * (1.f / 1024.f) + EPSF);
;             if (colg < NV) *(u32x2*)(proj + (size_t)row * PP + colg) = (u32x2){pk2(cv.x * rs, cv.y * rs), pk2(cv.z * rs, cv.w * rs)};
.LBB0_343:
	s_mov_b32 s0, 0x51eb851f
	v_mul_hi_i32 v0, v128, s0
	v_lshrrev_b32_e32 v1, 31, v0
	s_and_saveexec_b64 s[0:1], s[8:9]
	s_xor_b64 s[0:1], exec, s[0:1]
	v_ashrrev_i32_e32 v0, 3, v0
	v_add_u32_e32 v136, v0, v1
	v_mul_lo_u32 v0, v136, 25
	v_sub_u32_e32 v134, v128, v0
	s_andn2_saveexec_b64 s[0:1], s[0:1]
	v_ashrrev_i32_e32 v0, 6, v0
	v_add_u32_e32 v2, v0, v1
	s_movk_i32 s2, 0xff38
	v_mad_u64_u32 v[0:1], s[4:5], v2, s2, v[128:129]
	v_lshlrev_b32_e32 v1, 3, v128
	v_ashrrev_i32_e32 v134, 3, v0
	v_lshlrev_b32_e32 v0, 6, v2
	v_and_b32_e32 v1, 56, v1
	v_or3_b32 v136, v0, v1, v142
	s_or_b64 exec, exec, s[0:1]
	v_and_b32_e32 v242, 63, v180
	v_lshl_add_u32 v238, v136, 8, v151
	v_lshrrev_b32_e32 v243, 4, v242
	v_sub_u32_e32 v238, v238, v243
	v_lshrrev_b32_e32 v243, 3, v242
	v_add_u32_e32 v238, v238, v243
	v_lshlrev_b32_e32 v238, 2, v238
	global_load_dword v206, v238, s[22:23]
	global_load_dword v207, v238, s[22:23] offset:32
	global_load_dword v208, v238, s[22:23] offset:64
	global_load_dword v209, v238, s[22:23] offset:96
	global_load_dword v210, v238, s[22:23] offset:128
	global_load_dword v211, v238, s[22:23] offset:160
	global_load_dword v212, v238, s[22:23] offset:192
	global_load_dword v213, v238, s[22:23] offset:224
	global_load_dword v214, v238, s[22:23] offset:256
	global_load_dword v215, v238, s[22:23] offset:288
	global_load_dword v216, v238, s[22:23] offset:320
	global_load_dword v217, v238, s[22:23] offset:352
	global_load_dword v218, v238, s[22:23] offset:384
	global_load_dword v219, v238, s[22:23] offset:416
	global_load_dword v220, v238, s[22:23] offset:448
	global_load_dword v221, v238, s[22:23] offset:480
	v_readfirstlane_b32 s2, v144
	s_add_i32 s16, s2, 4
	s_lshl_b32 s6, s16, 9
	v_ashrrev_i32_e32 v137, 31, v136
	s_lshl_b32 s0, s2, 9
	s_ashr_i32 s7, s6, 31
	s_add_i32 s17, s2, 8
	v_lshlrev_b64 v[0:1], 19, v[136:137]
	s_ashr_i32 s1, s0, 31
	s_lshl_b32 s5, s2, 10
	s_lshl_b64 s[38:39], s[6:7], 1
	s_lshl_b32 s6, s17, 9
	v_lshl_add_u64 v[138:139], v[130:131], 0, v[0:1]
	s_lshl_b64 s[0:1], s[0:1], 1
	s_add_i32 s3, s5, 0
	s_lshl_b32 s16, s16, 10
	s_ashr_i32 s7, s6, 31
	s_add_i32 s2, s2, 12
	v_lshl_add_u64 v[2:3], v[138:139], 0, s[0:1]
	s_mov_b32 m0, s3
	s_add_i32 s18, s16, 0
	s_lshl_b64 s[40:41], s[6:7], 1
	s_lshl_b32 s17, s17, 10
	s_lshl_b32 s6, s2, 9
	global_load_lds_dwordx4 v[2:3], off
	v_lshl_add_u64 v[2:3], v[138:139], 0, s[38:39]
	s_mov_b32 m0, s18
	s_add_i32 s19, s17, 0
	s_ashr_i32 s7, s6, 31
	s_lshl_b32 s21, s2, 10
	global_load_lds_dwordx4 v[2:3], off
	v_lshl_add_u64 v[2:3], v[138:139], 0, s[40:41]
	s_mov_b32 m0, s19
	s_lshl_b64 s[42:43], s[6:7], 1
	s_add_i32 s2, s21, 0
	global_load_lds_dwordx4 v[2:3], off
	v_lshl_add_u64 v[2:3], v[138:139], 0, s[42:43]
	s_mov_b32 m0, s2
	v_ashrrev_i32_e32 v135, 31, v134
	global_load_lds_dwordx4 v[2:3], off
	v_lshlrev_b64 v[2:3], 18, v[134:135]
	v_lshl_add_u64 v[140:141], v[132:133], 0, v[2:3]
	v_lshl_add_u64 v[0:1], s[10:11], 0, v[0:1]
	v_lshl_add_u64 v[4:5], v[140:141], 0, s[0:1]
	s_add_i32 m0, s3, 0x4000
	v_lshl_add_u64 v[0:1], v[0:1], 0, v[160:161]
	s_mov_b64 s[6:7], 0x4000
	global_load_lds_dwordx4 v[4:5], off
	v_lshl_add_u64 v[4:5], v[140:141], 0, s[38:39]
	s_add_i32 m0, s18, 0x4000
	v_lshl_add_u64 v[0:1], v[0:1], 0, s[6:7]
	global_load_lds_dwordx4 v[4:5], off
	v_lshl_add_u64 v[4:5], v[0:1], 0, s[0:1]
	s_add_i32 m0, s3, 0x6000
	s_mov_b64 s[6:7], 0x2000
	global_load_lds_dwordx4 v[4:5], off
	v_lshl_add_u64 v[4:5], v[0:1], 0, s[38:39]
	s_add_i32 m0, s18, 0x6000
	s_mov_b32 s4, 1
	global_load_lds_dwordx4 v[4:5], off
	v_lshl_add_u64 v[4:5], v[0:1], 0, s[40:41]
	s_add_i32 m0, s19, 0x6000
	v_lshl_add_u64 v[0:1], v[0:1], 0, s[42:43]
	global_load_lds_dwordx4 v[4:5], off
	s_add_i32 m0, s2, 0x6000
	s_mov_b32 s86, 2
	global_load_lds_dwordx4 v[0:1], off
	v_lshl_add_u64 v[0:1], s[34:35], 0, v[2:3]
	v_lshl_add_u64 v[0:1], v[0:1], 0, v[160:161]
	v_lshl_add_u64 v[0:1], v[0:1], 0, s[6:7]
	v_lshl_add_u64 v[2:3], v[0:1], 0, s[0:1]
	s_add_i32 m0, s3, 0xa000
	v_lshl_add_u64 v[0:1], v[0:1], 0, s[38:39]
	global_load_lds_dwordx4 v[2:3], off
	s_add_i32 m0, s18, 0xa000
	s_mov_b32 s6, 0
	global_load_lds_dwordx4 v[0:1], off
	s_waitcnt vmcnt(6)
	s_barrier
	v_mov_b32_e32 v0, 0
	s_mov_b32 s33, 0
	v_mov_b32_e32 v1, v0
	v_mov_b32_e32 v2, v0
	v_mov_b32_e32 v3, v0
	v_mov_b32_e32 v4, v0
	v_mov_b32_e32 v5, v0
	v_mov_b32_e32 v6, v0
	v_mov_b32_e32 v7, v0
	v_mov_b32_e32 v8, v0
	v_mov_b32_e32 v9, v0
	v_mov_b32_e32 v10, v0
	v_mov_b32_e32 v11, v0
	v_mov_b32_e32 v12, v0
	v_mov_b32_e32 v13, v0
	v_mov_b32_e32 v14, v0
	v_mov_b32_e32 v15, v0
	v_mov_b32_e32 v16, v0
	v_mov_b32_e32 v17, v0
	v_mov_b32_e32 v18, v0
	v_mov_b32_e32 v19, v0
	v_mov_b32_e32 v20, v0
	v_mov_b32_e32 v21, v0
	v_mov_b32_e32 v22, v0
	v_mov_b32_e32 v23, v0
	v_mov_b32_e32 v24, v0
	v_mov_b32_e32 v25, v0
	v_mov_b32_e32 v26, v0
	v_mov_b32_e32 v27, v0
	v_mov_b32_e32 v28, v0
	v_mov_b32_e32 v29, v0
	v_mov_b32_e32 v30, v0
	v_mov_b32_e32 v31, v0
	v_mov_b32_e32 v64, v0
	v_mov_b32_e32 v65, v0
	v_mov_b32_e32 v66, v0
	v_mov_b32_e32 v67, v0
	v_mov_b32_e32 v68, v0
	v_mov_b32_e32 v69, v0
	v_mov_b32_e32 v70, v0
	v_mov_b32_e32 v71, v0
	v_mov_b32_e32 v72, v0
	v_mov_b32_e32 v73, v0
	v_mov_b32_e32 v74, v0
	v_mov_b32_e32 v75, v0
	v_mov_b32_e32 v76, v0
	v_mov_b32_e32 v77, v0
	v_mov_b32_e32 v78, v0
	v_mov_b32_e32 v79, v0
	v_mov_b32_e32 v80, v0
	v_mov_b32_e32 v81, v0
	v_mov_b32_e32 v82, v0
	v_mov_b32_e32 v83, v0
	v_mov_b32_e32 v84, v0
	v_mov_b32_e32 v85, v0
	v_mov_b32_e32 v86, v0
	v_mov_b32_e32 v87, v0
	v_mov_b32_e32 v88, v0
	v_mov_b32_e32 v89, v0
	v_mov_b32_e32 v90, v0
	v_mov_b32_e32 v91, v0
	v_mov_b32_e32 v92, v0
	v_mov_b32_e32 v93, v0
	v_mov_b32_e32 v94, v0
	v_mov_b32_e32 v95, v0
; template <int MODE>
; DI void gemm_phase(const Params& p, int layer, unsigned char* lds) {
;     ...
;     for (int kt = 0; kt < 32; ++kt) {
;       { const int kn_ = kt + 2 < 32 ? kt + 2 : 31; G_DMA(kn_, s2_); }
;       G_COMPUTE(s0_);
;       asm volatile("s_waitcnt vmcnt(6)" ::: "memory");
;       asm volatile("s_waitcnt lgkmcnt(0)" ::: "memory"); __builtin_amdgcn_s_barrier(); asm volatile("" ::: "memory");
;       const int t_ = s0_; s0_ = s1_; s1_ = s2_; s2_ = t_;
;     }
	v_mov_b32_e32 v32, v0
	v_mov_b32_e32 v33, v0
	v_mov_b32_e32 v34, v0
	v_mov_b32_e32 v35, v0
	v_mov_b32_e32 v36, v0
	v_mov_b32_e32 v37, v0
	v_mov_b32_e32 v38, v0
	v_mov_b32_e32 v39, v0
	v_mov_b32_e32 v40, v0
	v_mov_b32_e32 v41, v0
	v_mov_b32_e32 v42, v0
	v_mov_b32_e32 v43, v0
	v_mov_b32_e32 v44, v0
	v_mov_b32_e32 v45, v0
	v_mov_b32_e32 v46, v0
	v_mov_b32_e32 v47, v0
	v_mov_b32_e32 v48, v0
	v_mov_b32_e32 v49, v0
	v_mov_b32_e32 v50, v0
	v_mov_b32_e32 v51, v0
	v_mov_b32_e32 v52, v0
	v_mov_b32_e32 v53, v0
	v_mov_b32_e32 v54, v0
	v_mov_b32_e32 v55, v0
	v_mov_b32_e32 v56, v0
	v_mov_b32_e32 v57, v0
	v_mov_b32_e32 v58, v0
	v_mov_b32_e32 v59, v0
	v_mov_b32_e32 v60, v0
	v_mov_b32_e32 v61, v0
	v_mov_b32_e32 v62, v0
	v_mov_b32_e32 v63, v0
	v_mov_b32_e32 v96, v0
	v_mov_b32_e32 v97, v0
	v_mov_b32_e32 v98, v0
	v_mov_b32_e32 v99, v0
	v_mov_b32_e32 v100, v0
	v_mov_b32_e32 v101, v0
	v_mov_b32_e32 v102, v0
	v_mov_b32_e32 v103, v0
	v_mov_b32_e32 v104, v0
	v_mov_b32_e32 v105, v0
	v_mov_b32_e32 v106, v0
	v_mov_b32_e32 v107, v0
	v_mov_b32_e32 v108, v0
	v_mov_b32_e32 v109, v0
	v_mov_b32_e32 v110, v0
	v_mov_b32_e32 v111, v0
	v_mov_b32_e32 v112, v0
	v_mov_b32_e32 v113, v0
	v_mov_b32_e32 v114, v0
	v_mov_b32_e32 v115, v0
	v_mov_b32_e32 v116, v0
	v_mov_b32_e32 v117, v0
	v_mov_b32_e32 v118, v0
	v_mov_b32_e32 v119, v0
	v_mov_b32_e32 v120, v0
	v_mov_b32_e32 v121, v0
	v_mov_b32_e32 v122, v0
	v_mov_b32_e32 v123, v0
	v_mov_b32_e32 v124, v0
	v_mov_b32_e32 v125, v0
	v_mov_b32_e32 v126, v0
	v_mov_b32_e32 v127, v0
.LBB0_348:
	s_min_u32 s2, s33, 29
	s_add_i32 s2, s2, 2
	s_mov_b32 s87, s4
	s_mov_b32 s4, s6
	s_lshl_b32 s84, s2, 13
	s_lshl_b32 s6, s2, 14
	s_mul_i32 s2, s86, 0x6000
	s_mov_b32 s7, s85
	s_add_i32 s2, s2, 0
	v_lshl_add_u64 v[156:157], v[138:139], 0, s[6:7]
	s_add_i32 s3, s2, s5
	v_lshl_add_u64 v[158:159], v[156:157], 0, s[0:1]
	s_mov_b32 m0, s3
	s_add_i32 s6, s2, s16
	global_load_lds_dwordx4 v[158:159], off
	v_lshl_add_u64 v[158:159], v[156:157], 0, s[38:39]
	s_mov_b32 m0, s6
	s_mov_b32 s19, s85
	global_load_lds_dwordx4 v[158:159], off
	v_lshl_add_u64 v[158:159], v[156:157], 0, s[40:41]
	s_add_i32 m0, s2, s17
	v_lshl_add_u64 v[156:157], v[156:157], 0, s[42:43]
	global_load_lds_dwordx4 v[158:159], off
	s_add_i32 m0, s2, s21
	s_mul_i32 s2, s4, 0x6000
	global_load_lds_dwordx4 v[156:157], off
	v_lshl_add_u64 v[156:157], v[140:141], 0, s[84:85]
	v_lshl_add_u64 v[158:159], v[156:157], 0, s[0:1]
	s_add_i32 m0, s3, 0x4000
	v_lshl_add_u64 v[156:157], v[156:157], 0, s[38:39]
	global_load_lds_dwordx4 v[158:159], off
	s_add_i32 m0, s6, 0x4000
	s_add_i32 s6, s2, 0
	v_add_u32_e32 v135, s6, v152
	global_load_lds_dwordx4 v[156:157], off
	v_add3_u32 v137, v135, v145, v146
	v_add_u32_e32 v135, v135, v147
	ds_read_b128 v[156:159], v137 offset:16384
	ds_read_b128 v[162:165], v137 offset:18432
	ds_read_b128 v[166:169], v135
	ds_read_b128 v[170:173], v135 offset:2048
	ds_read_b128 v[174:177], v135 offset:4096
	ds_read_b128 v[202:205], v135 offset:6144
	s_waitcnt lgkmcnt(0)
	v_mfma_f32_32x32x16_bf16 v[112:127], v[156:159], v[166:169], v[112:127]
	v_add_u32_e32 v135, s6, v153
	v_add3_u32 v137, v135, v145, v146
	v_add_u32_e32 v135, v135, v147
	s_add_i32 s2, s33, 1
	s_min_u32 s2, s2, 29
	s_add_i32 s2, s2, 2
	s_lshl_b32 s18, s2, 14
	v_mfma_f32_32x32x16_bf16 v[96:111], v[156:159], v[170:173], v[96:111]
	s_lshl_b32 s84, s2, 13
	s_add_i32 s2, s6, s5
	s_mov_b32 m0, s2
	s_add_i32 s3, s6, s16
	s_add_i32 s33, s33, 2
	v_mfma_f32_32x32x16_bf16 v[48:63], v[156:159], v[174:177], v[48:63]
	v_mfma_f32_32x32x16_bf16 v[32:47], v[156:159], v[202:205], v[32:47]
	v_mfma_f32_32x32x16_bf16 v[80:95], v[162:165], v[166:169], v[80:95]
	v_mfma_f32_32x32x16_bf16 v[64:79], v[162:165], v[170:173], v[64:79]
	v_mfma_f32_32x32x16_bf16 v[16:31], v[162:165], v[174:177], v[16:31]
	v_mfma_f32_32x32x16_bf16 v[0:15], v[162:165], v[202:205], v[0:15]
	ds_read_b128 v[156:159], v137 offset:16384
	ds_read_b128 v[162:165], v137 offset:18432
	ds_read_b128 v[166:169], v135
	ds_read_b128 v[170:173], v135 offset:2048
	ds_read_b128 v[174:177], v135 offset:4096
	ds_read_b128 v[202:205], v135 offset:6144
	s_waitcnt vmcnt(6)
	s_waitcnt lgkmcnt(0)
	s_barrier
	s_waitcnt lgkmcnt(0)
	v_mfma_f32_32x32x16_bf16 v[112:127], v[156:159], v[166:169], v[112:127]
	v_mfma_f32_32x32x16_bf16 v[96:111], v[156:159], v[170:173], v[96:111]
	v_mfma_f32_32x32x16_bf16 v[48:63], v[156:159], v[174:177], v[48:63]
	v_mfma_f32_32x32x16_bf16 v[32:47], v[156:159], v[202:205], v[32:47]
	v_lshl_add_u64 v[156:157], v[138:139], 0, s[18:19]
	v_lshl_add_u64 v[158:159], v[156:157], 0, s[0:1]
	global_load_lds_dwordx4 v[158:159], off
	v_lshl_add_u64 v[158:159], v[156:157], 0, s[38:39]
	s_mov_b32 m0, s3
	s_nop 0
	global_load_lds_dwordx4 v[158:159], off
	v_lshl_add_u64 v[158:159], v[156:157], 0, s[40:41]
	s_add_i32 m0, s6, s17
	v_lshl_add_u64 v[156:157], v[156:157], 0, s[42:43]
	global_load_lds_dwordx4 v[158:159], off
	s_add_i32 m0, s6, s21
	v_mfma_f32_32x32x16_bf16 v[80:95], v[162:165], v[166:169], v[80:95]
	global_load_lds_dwordx4 v[156:157], off
	v_lshl_add_u64 v[156:157], v[140:141], 0, s[84:85]
	v_lshl_add_u64 v[158:159], v[156:157], 0, s[0:1]
	s_add_i32 m0, s2, 0x4000
	v_lshl_add_u64 v[156:157], v[156:157], 0, s[38:39]
	global_load_lds_dwordx4 v[158:159], off
	s_add_i32 m0, s3, 0x4000
	s_mul_i32 s2, s87, 0x6000
	global_load_lds_dwordx4 v[156:157], off
	v_mfma_f32_32x32x16_bf16 v[64:79], v[162:165], v[170:173], v[64:79]
	s_add_i32 s6, s2, 0
	v_add_u32_e32 v135, s6, v152
	v_add3_u32 v137, v135, v145, v146
	v_add_u32_e32 v135, v135, v147
	s_cmp_eq_u32 s33, 32
	v_mfma_f32_32x32x16_bf16 v[16:31], v[162:165], v[174:177], v[16:31]
	v_mfma_f32_32x32x16_bf16 v[0:15], v[162:165], v[202:205], v[0:15]
	ds_read_b128 v[156:159], v137 offset:16384
	ds_read_b128 v[162:165], v137 offset:18432
	ds_read_b128 v[166:169], v135
	ds_read_b128 v[170:173], v135 offset:2048
	ds_read_b128 v[174:177], v135 offset:4096
	ds_read_b128 v[202:205], v135 offset:6144
	v_add_u32_e32 v135, s6, v153
	v_add3_u32 v137, v135, v145, v146
	v_add_u32_e32 v135, v135, v147
	s_mov_b32 s6, s86
	s_mov_b32 s86, s87
	s_waitcnt lgkmcnt(0)
	v_mfma_f32_32x32x16_bf16 v[112:127], v[156:159], v[166:169], v[112:127]
	v_mfma_f32_32x32x16_bf16 v[96:111], v[156:159], v[170:173], v[96:111]
	v_mfma_f32_32x32x16_bf16 v[48:63], v[156:159], v[174:177], v[48:63]
	v_mfma_f32_32x32x16_bf16 v[32:47], v[156:159], v[202:205], v[32:47]
	v_mfma_f32_32x32x16_bf16 v[80:95], v[162:165], v[166:169], v[80:95]
	v_mfma_f32_32x32x16_bf16 v[64:79], v[162:165], v[170:173], v[64:79]
	v_mfma_f32_32x32x16_bf16 v[16:31], v[162:165], v[174:177], v[16:31]
	v_mfma_f32_32x32x16_bf16 v[0:15], v[162:165], v[202:205], v[0:15]
	ds_read_b128 v[156:159], v137 offset:16384
	ds_read_b128 v[162:165], v137 offset:18432
	ds_read_b128 v[166:169], v135
	ds_read_b128 v[170:173], v135 offset:2048
	ds_read_b128 v[174:177], v135 offset:4096
	ds_read_b128 v[202:205], v135 offset:6144
	s_waitcnt vmcnt(6)
	s_waitcnt lgkmcnt(0)
	s_barrier
; DI unsigned pk2(float lo, float hi) { f32x2 v = {lo, hi}; bfv2 b = __builtin_convertvector(v, bfv2); return __builtin_bit_cast(unsigned, b); }
; template <int MODE>
; DI void gemm_phase(const Params& p, int layer, unsigned char* lds) {
;     ...
;       G_COMPUTE(s0_);
;       asm volatile("s_waitcnt vmcnt(6)" ::: "memory");
;       asm volatile("s_waitcnt lgkmcnt(0)" ::: "memory"); __builtin_amdgcn_s_barrier(); asm volatile("" ::: "memory");
;       const int t_ = s0_; s0_ = s1_; s1_ = s2_; s2_ = t_;
;     }
;     asm volatile("s_waitcnt vmcnt(0)" ::: "memory"); __builtin_amdgcn_s_barrier(); asm volatile("" ::: "memory");
;     ...
;     {
;       float* Ct = (float*)lds + wid * (64 * 68);
;       const int rsub = lane >> 4, c4 = (lane & 15) * 4;
;       const int colg = n0 + wn * 64 + c4;
; #pragma unroll
;       for (int rd = 0; rd < 2; ++rd) {
; #pragma unroll
;         for (int mi = 0; mi < 2; ++mi)
; #pragma unroll
;           for (int ni = 0; ni < 2; ++ni)
; #pragma unroll
;             for (int g = 0; g < 4; ++g)
;               *(f32x4*)(Ct + (mi * 32 + r) * 68 + ni * 32 + 8 * g + 4 * hh) = (f32x4){acc[ni][2 * rd + mi][4 * g], acc[ni][2 * rd + mi][4 * g + 1], acc[ni][2 * rd + mi][4 * g + 2], acc[ni][2 * rd + mi][4 * g + 3]};
;         asm volatile("s_waitcnt lgkmcnt(0)" ::: "memory");
; #pragma unroll 4
;         for (int j = 0; j < 16; ++j) {
;           const int rl = 4 * j + rsub, row = m0 + wm * 128 + rd * 64 + rl;
;           const f32x4 cv = *(const f32x4*)(Ct + rl * 68 + c4);
;           if (MODE == 0) {
;             const float rs = rsqrtf(ssq[layer * T_TOK + row] * (1.f / 1024.f) + EPSF);
;             if (colg < NV) *(u32x2*)(proj + (size_t)row * PP + colg) = (u32x2){pk2(cv.x * rs, cv.y * rs), pk2(cv.z * rs, cv.w * rs)};
	s_waitcnt lgkmcnt(0)
	v_mfma_f32_32x32x16_bf16 v[112:127], v[156:159], v[166:169], v[112:127]
	v_mfma_f32_32x32x16_bf16 v[96:111], v[156:159], v[170:173], v[96:111]
	v_mfma_f32_32x32x16_bf16 v[48:63], v[156:159], v[174:177], v[48:63]
	v_mfma_f32_32x32x16_bf16 v[32:47], v[156:159], v[202:205], v[32:47]
	v_mfma_f32_32x32x16_bf16 v[80:95], v[162:165], v[166:169], v[80:95]
	v_mfma_f32_32x32x16_bf16 v[64:79], v[162:165], v[170:173], v[64:79]
	v_mfma_f32_32x32x16_bf16 v[16:31], v[162:165], v[174:177], v[16:31]
	v_mfma_f32_32x32x16_bf16 v[0:15], v[162:165], v[202:205], v[0:15]
	s_cbranch_scc0 .LBB0_348
	s_waitcnt vmcnt(0)
	s_barrier
	s_nop 2
	ds_write_b128 v154, v[112:115]
	ds_write_b128 v154, v[116:119] offset:32
	ds_write_b128 v154, v[120:123] offset:64
	ds_write_b128 v154, v[124:127] offset:96
	ds_write_b128 v154, v[80:83] offset:128
	ds_write_b128 v154, v[84:87] offset:160
	ds_write_b128 v154, v[88:91] offset:192
	ds_write_b128 v154, v[92:95] offset:224
	ds_write_b128 v154, v[96:99] offset:8704
	ds_write_b128 v154, v[100:103] offset:8736
	ds_write_b128 v154, v[104:107] offset:8768
	ds_write_b128 v154, v[108:111] offset:8800
	ds_write_b128 v154, v[64:67] offset:8832
	ds_write_b128 v154, v[68:71] offset:8864
	ds_write_b128 v154, v[72:75] offset:8896
	ds_write_b128 v154, v[76:79] offset:8928
	v_lshl_or_b32 v134, v134, 7, v148
	v_mov_b32_e32 v239, v134
	s_waitcnt lgkmcnt(0)
	v_lshlrev_b32_e32 v136, 8, v136
	s_movk_i32 s0, 0xc10
	v_ashrrev_i32_e32 v135, 31, v134
	v_cmp_gt_i32_e32 vcc, s0, v134
	v_lshl_add_u64 v[134:135], v[134:135], 1, s[46:47]
	v_add_u32_e32 v66, v150, v136
	v_add_u32_e32 v67, v151, v136
	v_and_b32_e32 v242, 63, v180
	v_lshrrev_b32_e32 v243, 3, v242
	v_and_b32_e32 v244, 7, v242
	v_and_b32_e32 v245, 0xffffffc0, v239
	v_lshl_or_b32 v245, v244, 3, v245
	s_movk_i32 s0, 0xc10
	v_cmp_gt_i32_e32 vcc, s0, v245
	v_mov_b32_e32 v238, v245
	v_mov_b32_e32 v239, 0
	v_lshl_add_u64 v[238:239], v[238:239], 1, s[46:47]
	v_lshrrev_b32_e32 v201, 4, v242
	v_sub_u32_e32 v201, v66, v201
	v_add_u32_e32 v201, v201, v243
	v_mad_i64_i32 v[240:241], s[0:1], v201, s12, v[238:239]
	v_lshrrev_b32_e32 v155, 6, v180
	v_mul_u32_u24_e32 v155, 0x4400, v155
	v_mul_u32_u24_e32 v201, 0x110, v243
	v_add_u32_e32 v155, v155, v201
	v_lshl_add_u32 v155, v244, 5, v155
	s_mov_b32 s2, 0xc400
	s_mov_b32 s3, 0
	s_and_saveexec_b64 s[38:39], vcc
	s_cbranch_execz .Lg0_r0_skip
; DI unsigned pk2(float lo, float hi) { f32x2 v = {lo, hi}; bfv2 b = __builtin_convertvector(v, bfv2); return __builtin_bit_cast(unsigned, b); }
; template <int MODE>
; DI void gemm_phase(const Params& p, int layer, unsigned char* lds) {
;     ...
;         asm volatile("s_waitcnt lgkmcnt(0)" ::: "memory");
; #pragma unroll 4
;         for (int j = 0; j < 16; ++j) {
;           const int rl = 4 * j + rsub, row = m0 + wm * 128 + rd * 64 + rl;
;           const f32x4 cv = *(const f32x4*)(Ct + rl * 68 + c4);
;           if (MODE == 0) {
;             const float rs = rsqrtf(ssq[layer * T_TOK + row] * (1.f / 1024.f) + EPSF);
;             if (colg < NV) *(u32x2*)(proj + (size_t)row * PP + colg) = (u32x2){pk2(cv.x * rs, cv.y * rs), pk2(cv.z * rs, cv.w * rs)};
	ds_read_b128 v[64:67], v155 offset:0
	ds_read_b128 v[68:71], v155 offset:16
	ds_read_b128 v[72:75], v155 offset:2176
	ds_read_b128 v[76:79], v155 offset:2192
	ds_read_b128 v[80:83], v155 offset:4352
	ds_read_b128 v[84:87], v155 offset:4368
	ds_read_b128 v[88:91], v155 offset:6528
	ds_read_b128 v[92:95], v155 offset:6544
	v_fmamk_f32 v156, v206, 0x3a800000, v181
	v_fmamk_f32 v158, v207, 0x3a800000, v181
	v_fmamk_f32 v162, v208, 0x3a800000, v181
	v_fmamk_f32 v164, v209, 0x3a800000, v181
	v_cmp_gt_f32_e64 s[0:1], s44, v156
	v_cmp_gt_f32_e64 s[4:5], s44, v158
	v_cmp_gt_f32_e64 s[6:7], s44, v162
	v_cmp_gt_f32_e64 s[18:19], s44, v164
	v_mul_f32_e32 v174, 0x4b800000, v156
	v_mul_f32_e32 v175, 0x4b800000, v158
	v_mul_f32_e32 v176, 0x4b800000, v162
	v_mul_f32_e32 v177, 0x4b800000, v164
	v_cndmask_b32_e64 v156, v156, v174, s[0:1]
	v_cndmask_b32_e64 v158, v158, v175, s[4:5]
	v_cndmask_b32_e64 v162, v162, v176, s[6:7]
	v_cndmask_b32_e64 v164, v164, v177, s[18:19]
	v_rsq_f32_e32 v156, v156
	v_rsq_f32_e32 v158, v158
	v_rsq_f32_e32 v162, v162
	v_rsq_f32_e32 v164, v164
	v_mul_f32_e32 v174, 0x45800000, v156
	v_mul_f32_e32 v175, 0x45800000, v158
	v_mul_f32_e32 v176, 0x45800000, v162
	v_mul_f32_e32 v177, 0x45800000, v164
	v_cndmask_b32_e64 v156, v156, v174, s[0:1]
	v_cndmask_b32_e64 v158, v158, v175, s[4:5]
	v_cndmask_b32_e64 v162, v162, v176, s[6:7]
	v_cndmask_b32_e64 v164, v164, v177, s[18:19]
	v_fmamk_f32 v166, v210, 0x3a800000, v181
	v_fmamk_f32 v168, v211, 0x3a800000, v181
	v_fmamk_f32 v170, v212, 0x3a800000, v181
	v_fmamk_f32 v172, v213, 0x3a800000, v181
	v_cmp_gt_f32_e64 s[0:1], s44, v166
	v_cmp_gt_f32_e64 s[4:5], s44, v168
	v_cmp_gt_f32_e64 s[6:7], s44, v170
	v_cmp_gt_f32_e64 s[18:19], s44, v172
	v_mul_f32_e32 v174, 0x4b800000, v166
	v_mul_f32_e32 v175, 0x4b800000, v168
	v_mul_f32_e32 v176, 0x4b800000, v170
	v_mul_f32_e32 v177, 0x4b800000, v172
	v_cndmask_b32_e64 v166, v166, v174, s[0:1]
	v_cndmask_b32_e64 v168, v168, v175, s[4:5]
	v_cndmask_b32_e64 v170, v170, v176, s[6:7]
	v_cndmask_b32_e64 v172, v172, v177, s[18:19]
	v_rsq_f32_e32 v166, v166
	v_rsq_f32_e32 v168, v168
	v_rsq_f32_e32 v170, v170
	v_rsq_f32_e32 v172, v172
	v_mul_f32_e32 v174, 0x45800000, v166
	v_mul_f32_e32 v175, 0x45800000, v168
	v_mul_f32_e32 v176, 0x45800000, v170
	v_mul_f32_e32 v177, 0x45800000, v172
	v_cndmask_b32_e64 v166, v166, v174, s[0:1]
	v_cndmask_b32_e64 v168, v168, v175, s[4:5]
	v_cndmask_b32_e64 v170, v170, v176, s[6:7]
	v_cndmask_b32_e64 v172, v172, v177, s[18:19]
	s_waitcnt lgkmcnt(6)
	v_pk_mul_f32 v[64:65], v[64:65], v[156:157] op_sel_hi:[1,0]
	v_pk_mul_f32 v[66:67], v[66:67], v[156:157] op_sel_hi:[1,0]
	v_pk_mul_f32 v[68:69], v[68:69], v[156:157] op_sel_hi:[1,0]
	v_pk_mul_f32 v[70:71], v[70:71], v[156:157] op_sel_hi:[1,0]
	v_cvt_pk_bf16_f32 v64, v64, v65
	v_cvt_pk_bf16_f32 v65, v66, v67
	v_cvt_pk_bf16_f32 v66, v68, v69
	v_cvt_pk_bf16_f32 v67, v70, v71
	global_store_dwordx4 v[240:241], v[64:67], off
	v_lshl_add_u64 v[240:241], v[240:241], 0, s[2:3]
	ds_read_b128 v[96:99], v155 offset:8704
	ds_read_b128 v[100:103], v155 offset:8720
	s_waitcnt lgkmcnt(6)
	v_pk_mul_f32 v[72:73], v[72:73], v[158:159] op_sel_hi:[1,0]
	v_pk_mul_f32 v[74:75], v[74:75], v[158:159] op_sel_hi:[1,0]
	v_pk_mul_f32 v[76:77], v[76:77], v[158:159] op_sel_hi:[1,0]
	v_pk_mul_f32 v[78:79], v[78:79], v[158:159] op_sel_hi:[1,0]
	v_cvt_pk_bf16_f32 v72, v72, v73
	v_cvt_pk_bf16_f32 v73, v74, v75
	v_cvt_pk_bf16_f32 v74, v76, v77
	v_cvt_pk_bf16_f32 v75, v78, v79
	global_store_dwordx4 v[240:241], v[72:75], off
	v_lshl_add_u64 v[240:241], v[240:241], 0, s[2:3]
	ds_read_b128 v[104:107], v155 offset:10880
	ds_read_b128 v[108:111], v155 offset:10896
	s_waitcnt lgkmcnt(6)
	v_pk_mul_f32 v[80:81], v[80:81], v[162:163] op_sel_hi:[1,0]
	v_pk_mul_f32 v[82:83], v[82:83], v[162:163] op_sel_hi:[1,0]
	v_pk_mul_f32 v[84:85], v[84:85], v[162:163] op_sel_hi:[1,0]
	v_pk_mul_f32 v[86:87], v[86:87], v[162:163] op_sel_hi:[1,0]
	v_cvt_pk_bf16_f32 v80, v80, v81
	v_cvt_pk_bf16_f32 v81, v82, v83
	v_cvt_pk_bf16_f32 v82, v84, v85
	v_cvt_pk_bf16_f32 v83, v86, v87
	global_store_dwordx4 v[240:241], v[80:83], off
	v_lshl_add_u64 v[240:241], v[240:241], 0, s[2:3]
	ds_read_b128 v[112:115], v155 offset:13056
	ds_read_b128 v[116:119], v155 offset:13072
	s_waitcnt lgkmcnt(6)
	v_pk_mul_f32 v[88:89], v[88:89], v[164:165] op_sel_hi:[1,0]
	v_pk_mul_f32 v[90:91], v[90:91], v[164:165] op_sel_hi:[1,0]
	v_pk_mul_f32 v[92:93], v[92:93], v[164:165] op_sel_hi:[1,0]
	v_pk_mul_f32 v[94:95], v[94:95], v[164:165] op_sel_hi:[1,0]
	v_cvt_pk_bf16_f32 v88, v88, v89
	v_cvt_pk_bf16_f32 v89, v90, v91
	v_cvt_pk_bf16_f32 v90, v92, v93
	v_cvt_pk_bf16_f32 v91, v94, v95
	global_store_dwordx4 v[240:241], v[88:91], off
	v_lshl_add_u64 v[240:241], v[240:241], 0, s[2:3]
	ds_read_b128 v[120:123], v155 offset:15232
	ds_read_b128 v[124:127], v155 offset:15248
	s_waitcnt lgkmcnt(6)
	v_pk_mul_f32 v[96:97], v[96:97], v[166:167] op_sel_hi:[1,0]
	v_pk_mul_f32 v[98:99], v[98:99], v[166:167] op_sel_hi:[1,0]
	v_pk_mul_f32 v[100:101], v[100:101], v[166:167] op_sel_hi:[1,0]
	v_pk_mul_f32 v[102:103], v[102:103], v[166:167] op_sel_hi:[1,0]
	v_cvt_pk_bf16_f32 v96, v96, v97
	v_cvt_pk_bf16_f32 v97, v98, v99
	v_cvt_pk_bf16_f32 v98, v100, v101
	v_cvt_pk_bf16_f32 v99, v102, v103
	global_store_dwordx4 v[240:241], v[96:99], off
	v_lshl_add_u64 v[240:241], v[240:241], 0, s[2:3]
	s_waitcnt lgkmcnt(4)
	v_pk_mul_f32 v[104:105], v[104:105], v[168:169] op_sel_hi:[1,0]
	v_pk_mul_f32 v[106:107], v[106:107], v[168:169] op_sel_hi:[1,0]
	v_pk_mul_f32 v[108:109], v[108:109], v[168:169] op_sel_hi:[1,0]
	v_pk_mul_f32 v[110:111], v[110:111], v[168:169] op_sel_hi:[1,0]
	v_cvt_pk_bf16_f32 v104, v104, v105
	v_cvt_pk_bf16_f32 v105, v106, v107
	v_cvt_pk_bf16_f32 v106, v108, v109
	v_cvt_pk_bf16_f32 v107, v110, v111
	global_store_dwordx4 v[240:241], v[104:107], off
	v_lshl_add_u64 v[240:241], v[240:241], 0, s[2:3]
	s_waitcnt lgkmcnt(2)
	v_pk_mul_f32 v[112:113], v[112:113], v[170:171] op_sel_hi:[1,0]
	v_pk_mul_f32 v[114:115], v[114:115], v[170:171] op_sel_hi:[1,0]
	v_pk_mul_f32 v[116:117], v[116:117], v[170:171] op_sel_hi:[1,0]
	v_pk_mul_f32 v[118:119], v[118:119], v[170:171] op_sel_hi:[1,0]
	v_cvt_pk_bf16_f32 v112, v112, v113
	v_cvt_pk_bf16_f32 v113, v114, v115
	v_cvt_pk_bf16_f32 v114, v116, v117
	v_cvt_pk_bf16_f32 v115, v118, v119
	global_store_dwordx4 v[240:241], v[112:115], off
	v_lshl_add_u64 v[240:241], v[240:241], 0, s[2:3]
	s_waitcnt lgkmcnt(0)
	v_pk_mul_f32 v[120:121], v[120:121], v[172:173] op_sel_hi:[1,0]
	v_pk_mul_f32 v[122:123], v[122:123], v[172:173] op_sel_hi:[1,0]
	v_pk_mul_f32 v[124:125], v[124:125], v[172:173] op_sel_hi:[1,0]
	v_pk_mul_f32 v[126:127], v[126:127], v[172:173] op_sel_hi:[1,0]
	v_cvt_pk_bf16_f32 v120, v120, v121
	v_cvt_pk_bf16_f32 v121, v122, v123
	v_cvt_pk_bf16_f32 v122, v124, v125
	v_cvt_pk_bf16_f32 v123, v126, v127
	global_store_dwordx4 v[240:241], v[120:123], off
	v_lshl_add_u64 v[240:241], v[240:241], 0, s[2:3]

; template <int MODE>
; DI void gemm_phase(const Params& p, int layer, unsigned char* lds) {
;     ...
;       for (int rd = 0; rd < 2; ++rd) {
; #pragma unroll
;         for (int mi = 0; mi < 2; ++mi)
; #pragma unroll
;           for (int ni = 0; ni < 2; ++ni)
; #pragma unroll
;             for (int g = 0; g < 4; ++g)
;               *(f32x4*)(Ct + (mi * 32 + r) * 68 + ni * 32 + 8 * g + 4 * hh) = (f32x4){acc[ni][2 * rd + mi][4 * g], acc[ni][2 * rd + mi][4 * g + 1], acc[ni][2 * rd + mi][4 * g + 2], acc[ni][2 * rd + mi][4 * g + 3]};
;         asm volatile("s_waitcnt lgkmcnt(0)" ::: "memory");
.LBB0_353:
	s_waitcnt lgkmcnt(0)
	ds_write_b128 v154, v[48:51]
	ds_write_b128 v154, v[52:55] offset:32
	ds_write_b128 v154, v[56:59] offset:64
	ds_write_b128 v154, v[60:63] offset:96
	ds_write_b128 v154, v[16:19] offset:128
	ds_write_b128 v154, v[20:23] offset:160
	ds_write_b128 v154, v[24:27] offset:192
	ds_write_b128 v154, v[28:31] offset:224
	ds_write_b128 v154, v[32:35] offset:8704
	ds_write_b128 v154, v[36:39] offset:8736
	ds_write_b128 v154, v[40:43] offset:8768
	ds_write_b128 v154, v[44:47] offset:8800
	ds_write_b128 v154, v[0:3] offset:8832
	ds_write_b128 v154, v[4:7] offset:8864
	ds_write_b128 v154, v[8:11] offset:8896
	ds_write_b128 v154, v[12:15] offset:8928
	s_waitcnt lgkmcnt(0)
	s_and_saveexec_b64 s[38:39], vcc
	s_cbranch_execz .Lg0_r1_skip
; DI unsigned pk2(float lo, float hi) { f32x2 v = {lo, hi}; bfv2 b = __builtin_convertvector(v, bfv2); return __builtin_bit_cast(unsigned, b); }
; template <int MODE>
; DI void gemm_phase(const Params& p, int layer, unsigned char* lds) {
;     ...
;         asm volatile("s_waitcnt lgkmcnt(0)" ::: "memory");
; #pragma unroll 4
;         for (int j = 0; j < 16; ++j) {
;           const int rl = 4 * j + rsub, row = m0 + wm * 128 + rd * 64 + rl;
;           const f32x4 cv = *(const f32x4*)(Ct + rl * 68 + c4);
;           if (MODE == 0) {
;             const float rs = rsqrtf(ssq[layer * T_TOK + row] * (1.f / 1024.f) + EPSF);
;             if (colg < NV) *(u32x2*)(proj + (size_t)row * PP + colg) = (u32x2){pk2(cv.x * rs, cv.y * rs), pk2(cv.z * rs, cv.w * rs)};
	ds_read_b128 v[64:67], v155 offset:0
	ds_read_b128 v[68:71], v155 offset:16
	ds_read_b128 v[72:75], v155 offset:2176
	ds_read_b128 v[76:79], v155 offset:2192
	ds_read_b128 v[80:83], v155 offset:4352
	ds_read_b128 v[84:87], v155 offset:4368
	ds_read_b128 v[88:91], v155 offset:6528
	ds_read_b128 v[92:95], v155 offset:6544
	v_fmamk_f32 v156, v214, 0x3a800000, v181
	v_fmamk_f32 v158, v215, 0x3a800000, v181
	v_fmamk_f32 v162, v216, 0x3a800000, v181
	v_fmamk_f32 v164, v217, 0x3a800000, v181
	v_cmp_gt_f32_e64 s[0:1], s44, v156
	v_cmp_gt_f32_e64 s[4:5], s44, v158
	v_cmp_gt_f32_e64 s[6:7], s44, v162
	v_cmp_gt_f32_e64 s[18:19], s44, v164
	v_mul_f32_e32 v174, 0x4b800000, v156
	v_mul_f32_e32 v175, 0x4b800000, v158
	v_mul_f32_e32 v176, 0x4b800000, v162
	v_mul_f32_e32 v177, 0x4b800000, v164
	v_cndmask_b32_e64 v156, v156, v174, s[0:1]
	v_cndmask_b32_e64 v158, v158, v175, s[4:5]
	v_cndmask_b32_e64 v162, v162, v176, s[6:7]
	v_cndmask_b32_e64 v164, v164, v177, s[18:19]
	v_rsq_f32_e32 v156, v156
	v_rsq_f32_e32 v158, v158
	v_rsq_f32_e32 v162, v162
	v_rsq_f32_e32 v164, v164
	v_mul_f32_e32 v174, 0x45800000, v156
	v_mul_f32_e32 v175, 0x45800000, v158
	v_mul_f32_e32 v176, 0x45800000, v162
	v_mul_f32_e32 v177, 0x45800000, v164
	v_cndmask_b32_e64 v156, v156, v174, s[0:1]
	v_cndmask_b32_e64 v158, v158, v175, s[4:5]
	v_cndmask_b32_e64 v162, v162, v176, s[6:7]
	v_cndmask_b32_e64 v164, v164, v177, s[18:19]
	v_fmamk_f32 v166, v218, 0x3a800000, v181
	v_fmamk_f32 v168, v219, 0x3a800000, v181
	v_fmamk_f32 v170, v220, 0x3a800000, v181
	v_fmamk_f32 v172, v221, 0x3a800000, v181
	v_cmp_gt_f32_e64 s[0:1], s44, v166
	v_cmp_gt_f32_e64 s[4:5], s44, v168
	v_cmp_gt_f32_e64 s[6:7], s44, v170
	v_cmp_gt_f32_e64 s[18:19], s44, v172
	v_mul_f32_e32 v174, 0x4b800000, v166
	v_mul_f32_e32 v175, 0x4b800000, v168
	v_mul_f32_e32 v176, 0x4b800000, v170
	v_mul_f32_e32 v177, 0x4b800000, v172
	v_cndmask_b32_e64 v166, v166, v174, s[0:1]
	v_cndmask_b32_e64 v168, v168, v175, s[4:5]
	v_cndmask_b32_e64 v170, v170, v176, s[6:7]
	v_cndmask_b32_e64 v172, v172, v177, s[18:19]
	v_rsq_f32_e32 v166, v166
	v_rsq_f32_e32 v168, v168
	v_rsq_f32_e32 v170, v170
	v_rsq_f32_e32 v172, v172
	v_mul_f32_e32 v174, 0x45800000, v166
	v_mul_f32_e32 v175, 0x45800000, v168
	v_mul_f32_e32 v176, 0x45800000, v170
	v_mul_f32_e32 v177, 0x45800000, v172
	v_cndmask_b32_e64 v166, v166, v174, s[0:1]
	v_cndmask_b32_e64 v168, v168, v175, s[4:5]
	v_cndmask_b32_e64 v170, v170, v176, s[6:7]
	v_cndmask_b32_e64 v172, v172, v177, s[18:19]
	s_waitcnt lgkmcnt(6)
	v_pk_mul_f32 v[64:65], v[64:65], v[156:157] op_sel_hi:[1,0]
	v_pk_mul_f32 v[66:67], v[66:67], v[156:157] op_sel_hi:[1,0]
	v_pk_mul_f32 v[68:69], v[68:69], v[156:157] op_sel_hi:[1,0]
	v_pk_mul_f32 v[70:71], v[70:71], v[156:157] op_sel_hi:[1,0]
	v_cvt_pk_bf16_f32 v64, v64, v65
	v_cvt_pk_bf16_f32 v65, v66, v67
	v_cvt_pk_bf16_f32 v66, v68, v69
	v_cvt_pk_bf16_f32 v67, v70, v71
	global_store_dwordx4 v[240:241], v[64:67], off
	v_lshl_add_u64 v[240:241], v[240:241], 0, s[2:3]
	ds_read_b128 v[96:99], v155 offset:8704
	ds_read_b128 v[100:103], v155 offset:8720
	s_waitcnt lgkmcnt(6)
	v_pk_mul_f32 v[72:73], v[72:73], v[158:159] op_sel_hi:[1,0]
	v_pk_mul_f32 v[74:75], v[74:75], v[158:159] op_sel_hi:[1,0]
	v_pk_mul_f32 v[76:77], v[76:77], v[158:159] op_sel_hi:[1,0]
	v_pk_mul_f32 v[78:79], v[78:79], v[158:159] op_sel_hi:[1,0]
	v_cvt_pk_bf16_f32 v72, v72, v73
	v_cvt_pk_bf16_f32 v73, v74, v75
	v_cvt_pk_bf16_f32 v74, v76, v77
	v_cvt_pk_bf16_f32 v75, v78, v79
	global_store_dwordx4 v[240:241], v[72:75], off
	v_lshl_add_u64 v[240:241], v[240:241], 0, s[2:3]
	ds_read_b128 v[104:107], v155 offset:10880
	ds_read_b128 v[108:111], v155 offset:10896
	s_waitcnt lgkmcnt(6)
	v_pk_mul_f32 v[80:81], v[80:81], v[162:163] op_sel_hi:[1,0]
	v_pk_mul_f32 v[82:83], v[82:83], v[162:163] op_sel_hi:[1,0]
	v_pk_mul_f32 v[84:85], v[84:85], v[162:163] op_sel_hi:[1,0]
	v_pk_mul_f32 v[86:87], v[86:87], v[162:163] op_sel_hi:[1,0]
	v_cvt_pk_bf16_f32 v80, v80, v81
	v_cvt_pk_bf16_f32 v81, v82, v83
	v_cvt_pk_bf16_f32 v82, v84, v85
	v_cvt_pk_bf16_f32 v83, v86, v87
	global_store_dwordx4 v[240:241], v[80:83], off
	v_lshl_add_u64 v[240:241], v[240:241], 0, s[2:3]
	ds_read_b128 v[112:115], v155 offset:13056
	ds_read_b128 v[116:119], v155 offset:13072
	s_waitcnt lgkmcnt(6)
	v_pk_mul_f32 v[88:89], v[88:89], v[164:165] op_sel_hi:[1,0]
	v_pk_mul_f32 v[90:91], v[90:91], v[164:165] op_sel_hi:[1,0]
	v_pk_mul_f32 v[92:93], v[92:93], v[164:165] op_sel_hi:[1,0]
	v_pk_mul_f32 v[94:95], v[94:95], v[164:165] op_sel_hi:[1,0]
	v_cvt_pk_bf16_f32 v88, v88, v89
	v_cvt_pk_bf16_f32 v89, v90, v91
	v_cvt_pk_bf16_f32 v90, v92, v93
	v_cvt_pk_bf16_f32 v91, v94, v95
	global_store_dwordx4 v[240:241], v[88:91], off
	v_lshl_add_u64 v[240:241], v[240:241], 0, s[2:3]
	ds_read_b128 v[120:123], v155 offset:15232
	ds_read_b128 v[124:127], v155 offset:15248
	s_waitcnt lgkmcnt(6)
	v_pk_mul_f32 v[96:97], v[96:97], v[166:167] op_sel_hi:[1,0]
	v_pk_mul_f32 v[98:99], v[98:99], v[166:167] op_sel_hi:[1,0]
	v_pk_mul_f32 v[100:101], v[100:101], v[166:167] op_sel_hi:[1,0]
	v_pk_mul_f32 v[102:103], v[102:103], v[166:167] op_sel_hi:[1,0]
	v_cvt_pk_bf16_f32 v96, v96, v97
	v_cvt_pk_bf16_f32 v97, v98, v99
	v_cvt_pk_bf16_f32 v98, v100, v101
	v_cvt_pk_bf16_f32 v99, v102, v103
	global_store_dwordx4 v[240:241], v[96:99], off
	v_lshl_add_u64 v[240:241], v[240:241], 0, s[2:3]
	s_waitcnt lgkmcnt(4)
	v_pk_mul_f32 v[104:105], v[104:105], v[168:169] op_sel_hi:[1,0]
	v_pk_mul_f32 v[106:107], v[106:107], v[168:169] op_sel_hi:[1,0]
	v_pk_mul_f32 v[108:109], v[108:109], v[168:169] op_sel_hi:[1,0]
	v_pk_mul_f32 v[110:111], v[110:111], v[168:169] op_sel_hi:[1,0]
	v_cvt_pk_bf16_f32 v104, v104, v105
	v_cvt_pk_bf16_f32 v105, v106, v107
	v_cvt_pk_bf16_f32 v106, v108, v109
	v_cvt_pk_bf16_f32 v107, v110, v111
	global_store_dwordx4 v[240:241], v[104:107], off
	v_lshl_add_u64 v[240:241], v[240:241], 0, s[2:3]
	s_waitcnt lgkmcnt(2)
	v_pk_mul_f32 v[112:113], v[112:113], v[170:171] op_sel_hi:[1,0]
	v_pk_mul_f32 v[114:115], v[114:115], v[170:171] op_sel_hi:[1,0]
	v_pk_mul_f32 v[116:117], v[116:117], v[170:171] op_sel_hi:[1,0]
	v_pk_mul_f32 v[118:119], v[118:119], v[170:171] op_sel_hi:[1,0]
	v_cvt_pk_bf16_f32 v112, v112, v113
	v_cvt_pk_bf16_f32 v113, v114, v115
	v_cvt_pk_bf16_f32 v114, v116, v117
	v_cvt_pk_bf16_f32 v115, v118, v119
	global_store_dwordx4 v[240:241], v[112:115], off
	v_lshl_add_u64 v[240:241], v[240:241], 0, s[2:3]
	s_waitcnt lgkmcnt(0)
	v_pk_mul_f32 v[120:121], v[120:121], v[172:173] op_sel_hi:[1,0]
	v_pk_mul_f32 v[122:123], v[122:123], v[172:173] op_sel_hi:[1,0]
	v_pk_mul_f32 v[124:125], v[124:125], v[172:173] op_sel_hi:[1,0]
	v_pk_mul_f32 v[126:127], v[126:127], v[172:173] op_sel_hi:[1,0]
	v_cvt_pk_bf16_f32 v120, v120, v121
	v_cvt_pk_bf16_f32 v121, v122, v123
	v_cvt_pk_bf16_f32 v122, v124, v125
	v_cvt_pk_bf16_f32 v123, v126, v127
	global_store_dwordx4 v[240:241], v[120:123], off
	v_lshl_add_u64 v[240:241], v[240:241], 0, s[2:3]
